# pipelined group-barrier polling with dedicated VGPRs v252-v254 (next_free_vgpr 256), no v0/v1 save
# speedup vs baseline: 1.0057x; 1.0001x over previous
.LBB0_434:
	s_or_b64 exec, exec, s[4:5]
	s_waitcnt lgkmcnt(0)
	s_mov_b64 s[6:7], s[68:69]
	s_waitcnt vmcnt(0)
	s_barrier
	s_and_saveexec_b64 s[0:1], s[70:71]
	s_xor_b64 s[4:5], exec, s[0:1]
	v_writelane_b32 v250, s22, 11
	s_cbranch_execz .LBB0_488
	v_writelane_b32 v250, s8, 44
	v_writelane_b32 v250, s9, 45
	v_writelane_b32 v250, s10, 46
	v_writelane_b32 v250, s11, 47
	v_writelane_b32 v250, s14, 50
	v_writelane_b32 v250, s15, 51
	s_load_dwordx2 s[8:9], s[68:69], 0xb8
	v_mov_b32_e32 v252, 0
	v_mov_b32_e32 v253, 1
	v_readlane_b32 s10, v250, 63
	v_readlane_b32 s11, v250, 61
	v_readlane_b32 s14, v250, 59
	s_mov_b32 s15, 0
	s_waitcnt lgkmcnt(0)
	s_add_u32 s8, s8, s10
	s_addc_u32 s9, s9, 0
	s_cmp_lg_u32 s11, 0
	s_cbranch_scc1 .Lgb1_known
	global_load_dword v254, v252, s[8:9] offset:128 sc1
	s_waitcnt vmcnt(0)
	v_readfirstlane_b32 s10, v254
	s_sub_u32 s11, s10, 1
	s_and_b32 s11, s11, s10
	s_cmp_eq_u32 s11, 0
	s_cselect_b32 s11, 2, 1
	s_cmp_eq_u32 s10, 0
	s_cselect_b32 s11, 1, s11
	v_writelane_b32 v250, s11, 61
	s_nop 0
.Lgb1_known:
	v_readlane_b32 s10, v250, 60
	v_mov_b32_e32 v254, 0
	s_add_u32 s10, s10, s14
	v_writelane_b32 v250, s10, 60
	s_cmp_eq_u32 s11, 2
	s_cbranch_scc1 .Lgb1_pure
	buffer_wbl2 sc1
	s_waitcnt vmcnt(0)
	global_atomic_add v252, v253, s[8:9]
	s_branch .Lgb1_spin
.Lgb1_pure:
	buffer_inv sc1
	global_atomic_add v252, v253, s[8:9]
.Lgb1_spin:
	global_load_dword v254, v252, s[8:9] sc1
	s_add_u32 s15, s15, 1
	s_waitcnt vmcnt(2)
	v_cmp_gt_u32_e32 vcc, s10, v254
	s_cbranch_vccz .Lgb1_rel
	s_cmp_lt_u32 s15, 0x400000
	s_cbranch_scc0 .Lgb1_rel
	s_sleep 2
	s_branch .Lgb1_spin

.Lgb1_done:
	v_readlane_b32 s8, v250, 44
	v_readlane_b32 s9, v250, 45
	v_readlane_b32 s10, v250, 46
	v_readlane_b32 s11, v250, 47
	v_readlane_b32 s14, v250, 50
	v_readlane_b32 s15, v250, 51
	s_branch .LBB0_488

.LBB0_518:
	s_mov_b64 s[6:7], s[68:69]
	s_waitcnt vmcnt(0)
	s_waitcnt vmcnt(0) lgkmcnt(0)
	s_barrier
	s_and_saveexec_b64 s[4:5], s[70:71]
	s_xor_b64 s[4:5], exec, s[4:5]
	s_cbranch_execz .LBB0_571
	v_writelane_b32 v250, s8, 44
	v_writelane_b32 v250, s9, 45
	v_writelane_b32 v250, s10, 46
	v_writelane_b32 v250, s11, 47
	v_writelane_b32 v250, s14, 50
	v_writelane_b32 v250, s15, 51
	s_load_dwordx2 s[8:9], s[68:69], 0xb8
	v_mov_b32_e32 v252, 0
	v_mov_b32_e32 v253, 1
	v_readlane_b32 s10, v250, 63
	v_readlane_b32 s11, v250, 61
	v_readlane_b32 s14, v250, 59
	s_mov_b32 s15, 0
	s_waitcnt lgkmcnt(0)
	s_add_u32 s8, s8, s10
	s_addc_u32 s9, s9, 0
	s_cmp_lg_u32 s11, 0
	s_cbranch_scc1 .Lgb2_known
	global_load_dword v254, v252, s[8:9] offset:128 sc1
	s_waitcnt vmcnt(0)
	v_readfirstlane_b32 s10, v254
	s_sub_u32 s11, s10, 1
	s_and_b32 s11, s11, s10
	s_cmp_eq_u32 s11, 0
	s_cselect_b32 s11, 2, 1
	s_cmp_eq_u32 s10, 0
	s_cselect_b32 s11, 1, s11
	v_writelane_b32 v250, s11, 61
	s_nop 0

.Lgb2_done:
	v_readlane_b32 s8, v250, 44
	v_readlane_b32 s9, v250, 45
	v_readlane_b32 s10, v250, 46
	v_readlane_b32 s11, v250, 47
	v_readlane_b32 s14, v250, 50
	v_readlane_b32 s15, v250, 51

.LBB0_604:
	s_mov_b64 s[4:5], s[68:69]
	s_waitcnt vmcnt(0)
	s_waitcnt lgkmcnt(0)
	s_barrier
	s_and_saveexec_b64 s[0:1], s[70:71]
	s_xor_b64 s[2:3], exec, s[0:1]
	v_readlane_b32 s22, v250, 11
	s_cbranch_execz .LBB0_658
	v_writelane_b32 v250, s8, 44
	v_writelane_b32 v250, s9, 45
	v_writelane_b32 v250, s10, 46
	v_writelane_b32 v250, s11, 47
	v_writelane_b32 v250, s14, 50
	v_writelane_b32 v250, s15, 51
	s_load_dwordx2 s[8:9], s[68:69], 0xb8
	v_mov_b32_e32 v252, 0
	v_mov_b32_e32 v253, 1
	v_readlane_b32 s10, v250, 63
	v_readlane_b32 s11, v250, 61
	v_readlane_b32 s14, v250, 59
	s_mov_b32 s15, 0
	s_waitcnt lgkmcnt(0)
	s_add_u32 s8, s8, s10
	s_addc_u32 s9, s9, 0
	s_cmp_lg_u32 s11, 0
	s_cbranch_scc1 .Lgb3_known
	global_load_dword v254, v252, s[8:9] offset:128 sc1
	s_waitcnt vmcnt(0)
	v_readfirstlane_b32 s10, v254
	s_sub_u32 s11, s10, 1
	s_and_b32 s11, s11, s10
	s_cmp_eq_u32 s11, 0
	s_cselect_b32 s11, 2, 1
	s_cmp_eq_u32 s10, 0
	s_cselect_b32 s11, 1, s11
	v_writelane_b32 v250, s11, 61
	s_nop 0

.LBB0_884:
	s_waitcnt lgkmcnt(0)
	s_mov_b64 s[4:5], s[68:69]
	s_waitcnt vmcnt(0)
	s_waitcnt vmcnt(0)
	s_barrier
	s_and_saveexec_b64 s[0:1], s[70:71]
	s_xor_b64 s[2:3], exec, s[0:1]
	s_cbranch_execz .LBB0_937
	v_writelane_b32 v250, s8, 44
	v_writelane_b32 v250, s9, 45
	v_writelane_b32 v250, s10, 46
	v_writelane_b32 v250, s11, 47
	v_writelane_b32 v250, s14, 50
	v_writelane_b32 v250, s15, 51
	s_load_dwordx2 s[8:9], s[68:69], 0xb8
	v_mov_b32_e32 v252, 0
	v_mov_b32_e32 v253, 1
	v_readlane_b32 s10, v250, 63
	v_readlane_b32 s11, v250, 61
	v_readlane_b32 s14, v250, 59
	s_mov_b32 s15, 0
	s_waitcnt lgkmcnt(0)
	s_add_u32 s8, s8, s10
	s_addc_u32 s9, s9, 0
	s_cmp_lg_u32 s11, 0
	s_cbranch_scc1 .Lgb4_known
	global_load_dword v254, v252, s[8:9] offset:128 sc1
	s_waitcnt vmcnt(0)
	v_readfirstlane_b32 s10, v254
	s_sub_u32 s11, s10, 1
	s_and_b32 s11, s11, s10
	s_cmp_eq_u32 s11, 0
	s_cselect_b32 s11, 2, 1
	s_cmp_eq_u32 s10, 0
	s_cselect_b32 s11, 1, s11
	v_writelane_b32 v250, s11, 61
	s_nop 0

.LBB0_968:
	s_mov_b64 s[4:5], s[68:69]
	s_waitcnt vmcnt(0)
	s_waitcnt vmcnt(0) lgkmcnt(0)
	s_barrier
	s_and_saveexec_b64 s[2:3], s[70:71]
	v_readlane_b32 s48, v251, 9
	s_cbranch_execz .LBB0_1020
	v_writelane_b32 v250, s8, 44
	v_writelane_b32 v250, s9, 45
	v_writelane_b32 v250, s10, 46
	v_writelane_b32 v250, s11, 47
	v_writelane_b32 v250, s14, 50
	v_writelane_b32 v250, s15, 51
	s_load_dwordx2 s[8:9], s[68:69], 0xb8
	v_mov_b32_e32 v252, 0
	v_mov_b32_e32 v253, 1
	v_readlane_b32 s10, v250, 63
	v_readlane_b32 s11, v250, 61
	v_readlane_b32 s14, v250, 59
	s_mov_b32 s15, 0
	s_waitcnt lgkmcnt(0)
	s_add_u32 s8, s8, s10
	s_addc_u32 s9, s9, 0
	s_cmp_lg_u32 s11, 0
	s_cbranch_scc1 .Lgb5_known
	global_load_dword v254, v252, s[8:9] offset:128 sc1
	s_waitcnt vmcnt(0)
	v_readfirstlane_b32 s10, v254
	s_sub_u32 s11, s10, 1
	s_and_b32 s11, s11, s10
	s_cmp_eq_u32 s11, 0
	s_cselect_b32 s11, 2, 1
	s_cmp_eq_u32 s10, 0
	s_cselect_b32 s11, 1, s11
	v_writelane_b32 v250, s11, 61
	s_nop 0

.LBB0_1039:
	s_or_b64 exec, exec, s[2:3]
	s_mov_b64 s[4:5], s[68:69]
	s_waitcnt vmcnt(0)
	s_barrier
	s_and_saveexec_b64 s[0:1], s[70:71]
	s_xor_b64 s[2:3], exec, s[0:1]
	s_cbranch_execz .LBB0_1092
	v_writelane_b32 v250, s8, 44
	v_writelane_b32 v250, s9, 45
	v_writelane_b32 v250, s10, 46
	v_writelane_b32 v250, s11, 47
	v_writelane_b32 v250, s14, 50
	v_writelane_b32 v250, s15, 51
	s_load_dwordx2 s[8:9], s[68:69], 0xb8
	v_mov_b32_e32 v252, 0
	v_mov_b32_e32 v253, 1
	v_readlane_b32 s10, v250, 63
	v_readlane_b32 s11, v250, 61
	v_readlane_b32 s14, v250, 59
	s_mov_b32 s15, 0
	s_waitcnt lgkmcnt(0)
	s_add_u32 s8, s8, s10
	s_addc_u32 s9, s9, 0
	s_cmp_lg_u32 s11, 0
	s_cbranch_scc1 .Lgb6_known
	global_load_dword v254, v252, s[8:9] offset:128 sc1
	s_waitcnt vmcnt(0)
	v_readfirstlane_b32 s10, v254
	s_sub_u32 s11, s10, 1
	s_and_b32 s11, s11, s10
	s_cmp_eq_u32 s11, 0
	s_cselect_b32 s11, 2, 1
	s_cmp_eq_u32 s10, 0
	s_cselect_b32 s11, 1, s11
	v_writelane_b32 v250, s11, 61
	s_nop 0

.LBB0_1443:
	s_setprio 0
	v_readlane_b32 s68, v251, 44
	v_readlane_b32 s69, v251, 45
	s_mov_b64 s[4:5], s[68:69]
	s_waitcnt vmcnt(0)
	v_readlane_b32 s70, v251, 46
	v_readlane_b32 s71, v251, 47
	s_barrier
	s_and_saveexec_b64 s[0:1], s[70:71]
	v_readlane_b32 s34, v251, 37
	v_readlane_b32 s40, v251, 42
	s_xor_b64 s[2:3], exec, s[0:1]
	v_readlane_b32 s72, v251, 48
	v_readlane_b32 s30, v251, 34
	v_readlane_b32 s73, v251, 36
	v_readlane_b32 s35, v251, 38
	v_readlane_b32 s51, v251, 39
	v_readlane_b32 s36, v251, 40
	v_readlane_b32 s37, v251, 41
	s_movk_i32 s67, 0x4000
	s_mov_b32 s38, 0x800000
	s_mov_b32 s39, 0x2aaaaaab
	v_readlane_b32 s41, v251, 43
	v_readlane_b32 s31, v251, 35
	s_cbranch_execz .LBB0_1496
	v_writelane_b32 v250, s8, 44
	v_writelane_b32 v250, s9, 45
	v_writelane_b32 v250, s10, 46
	v_writelane_b32 v250, s11, 47
	v_writelane_b32 v250, s14, 50
	v_writelane_b32 v250, s15, 51
	s_load_dwordx2 s[8:9], s[68:69], 0xb8
	v_mov_b32_e32 v252, 0
	v_mov_b32_e32 v253, 1
	v_readlane_b32 s10, v250, 63
	v_readlane_b32 s11, v250, 61
	v_readlane_b32 s14, v250, 59
	s_mov_b32 s15, 0
	s_waitcnt lgkmcnt(0)
	s_add_u32 s8, s8, s10
	s_addc_u32 s9, s9, 0
	s_cmp_lg_u32 s11, 0
	s_cbranch_scc1 .Lgb7_known
	global_load_dword v254, v252, s[8:9] offset:128 sc1
	s_waitcnt vmcnt(0)
	v_readfirstlane_b32 s10, v254
	s_sub_u32 s11, s10, 1
	s_and_b32 s11, s11, s10
	s_cmp_eq_u32 s11, 0
	s_cselect_b32 s11, 2, 1
	s_cmp_eq_u32 s10, 0
	s_cselect_b32 s11, 1, s11
	v_writelane_b32 v250, s11, 61
	s_nop 0

.LBB0_1610:
	s_mov_b64 s[4:5], s[68:69]
	s_waitcnt vmcnt(0)
	s_waitcnt vmcnt(0) lgkmcnt(0)
	s_barrier
	s_and_saveexec_b64 s[0:1], s[70:71]
	s_xor_b64 s[2:3], exec, s[0:1]
	s_cbranch_execz .LBB0_1663
	v_writelane_b32 v250, s8, 44
	v_writelane_b32 v250, s9, 45
	v_writelane_b32 v250, s10, 46
	v_writelane_b32 v250, s11, 47
	v_writelane_b32 v250, s14, 50
	v_writelane_b32 v250, s15, 51
	s_load_dwordx2 s[8:9], s[68:69], 0xb8
	v_mov_b32_e32 v252, 0
	v_mov_b32_e32 v253, 1
	v_readlane_b32 s10, v250, 63
	v_readlane_b32 s11, v250, 61
	v_readlane_b32 s14, v250, 59
	s_mov_b32 s15, 0
	s_waitcnt lgkmcnt(0)
	s_add_u32 s8, s8, s10
	s_addc_u32 s9, s9, 0
	s_cmp_lg_u32 s11, 0
	s_cbranch_scc1 .Lgb9_known
	global_load_dword v254, v252, s[8:9] offset:128 sc1
	s_waitcnt vmcnt(0)
	v_readfirstlane_b32 s10, v254
	s_sub_u32 s11, s10, 1
	s_and_b32 s11, s11, s10
	s_cmp_eq_u32 s11, 0
	s_cselect_b32 s11, 2, 1
	s_cmp_eq_u32 s10, 0
	s_cselect_b32 s11, 1, s11
	v_writelane_b32 v250, s11, 61
	s_nop 0

.LBB0_2018:
	s_setprio 0
	s_mov_b64 s[4:5], s[68:69]
	s_waitcnt vmcnt(0)
	s_barrier
	s_and_saveexec_b64 s[0:1], s[70:71]
	s_xor_b64 s[2:3], exec, s[0:1]
	s_cbranch_execz .LBB0_2071
	v_writelane_b32 v250, s8, 44
	v_writelane_b32 v250, s9, 45
	v_writelane_b32 v250, s10, 46
	v_writelane_b32 v250, s11, 47
	v_writelane_b32 v250, s14, 50
	v_writelane_b32 v250, s15, 51
	s_load_dwordx2 s[8:9], s[68:69], 0xb8
	v_mov_b32_e32 v252, 0
	v_mov_b32_e32 v253, 1
	v_readlane_b32 s10, v250, 63
	v_readlane_b32 s11, v250, 61
	v_readlane_b32 s14, v250, 59
	s_mov_b32 s15, 0
	s_waitcnt lgkmcnt(0)
	s_add_u32 s8, s8, s10
	s_addc_u32 s9, s9, 0
	s_cmp_lg_u32 s11, 0
	s_cbranch_scc1 .Lgb12_known
	global_load_dword v254, v252, s[8:9] offset:128 sc1
	s_waitcnt vmcnt(0)
	v_readfirstlane_b32 s10, v254
	s_sub_u32 s11, s10, 1
	s_and_b32 s11, s11, s10
	s_cmp_eq_u32 s11, 0
	s_cselect_b32 s11, 2, 1
	s_cmp_eq_u32 s10, 0
	s_cselect_b32 s11, 1, s11
	v_writelane_b32 v250, s11, 61
	s_nop 0

.LBB0_2102:
	v_writelane_b32 v250, s8, 44
	v_writelane_b32 v250, s9, 45
	v_writelane_b32 v250, s10, 46
	v_writelane_b32 v250, s11, 47
	v_writelane_b32 v250, s14, 50
	v_writelane_b32 v250, s15, 51
	s_load_dwordx2 s[8:9], s[68:69], 0xb8
	v_mov_b32_e32 v252, 0
	v_mov_b32_e32 v253, 1
	v_readlane_b32 s10, v250, 63
	v_readlane_b32 s11, v250, 61
	v_readlane_b32 s14, v250, 59
	s_mov_b32 s15, 0
	s_waitcnt lgkmcnt(0)
	s_add_u32 s8, s8, s10
	s_addc_u32 s9, s9, 0
	s_cmp_lg_u32 s11, 0
	s_cbranch_scc1 .Lgb13_known
	global_load_dword v254, v252, s[8:9] offset:128 sc1
	s_waitcnt vmcnt(0)
	v_readfirstlane_b32 s10, v254
	s_sub_u32 s11, s10, 1
	s_and_b32 s11, s11, s10
	s_cmp_eq_u32 s11, 0
	s_cselect_b32 s11, 2, 1
	s_cmp_eq_u32 s10, 0
	s_cselect_b32 s11, 1, s11
	v_writelane_b32 v250, s11, 61
	s_nop 0

	.amdhsa_kernel _Z4mega6Params
		.amdhsa_group_segment_fixed_size 0
		.amdhsa_private_segment_fixed_size 0
		.amdhsa_kernarg_size 448
		.amdhsa_user_sgpr_count 2
		.amdhsa_user_sgpr_dispatch_ptr 0
		.amdhsa_user_sgpr_queue_ptr 0
		.amdhsa_user_sgpr_kernarg_segment_ptr 1
		.amdhsa_user_sgpr_dispatch_id 0
		.amdhsa_user_sgpr_kernarg_preload_length 0
		.amdhsa_user_sgpr_kernarg_preload_offset 0
		.amdhsa_user_sgpr_private_segment_size 0
		.amdhsa_uses_dynamic_stack 0
		.amdhsa_enable_private_segment 0
		.amdhsa_system_sgpr_workgroup_id_x 1
		.amdhsa_system_sgpr_workgroup_id_y 0
		.amdhsa_system_sgpr_workgroup_id_z 0
		.amdhsa_system_sgpr_workgroup_info 0
		.amdhsa_system_vgpr_workitem_id 2
		.amdhsa_next_free_vgpr 256
		.amdhsa_next_free_sgpr 100
		.amdhsa_accum_offset 256
		.amdhsa_reserve_vcc 1
		.amdhsa_float_round_mode_32 0
		.amdhsa_float_round_mode_16_64 0
		.amdhsa_float_denorm_mode_32 3
		.amdhsa_float_denorm_mode_16_64 3
		.amdhsa_dx10_clamp 1
		.amdhsa_ieee_mode 1
		.amdhsa_fp16_overflow 0
		.amdhsa_tg_split 0
		.amdhsa_exception_fp_ieee_invalid_op 0
		.amdhsa_exception_fp_denorm_src 0
		.amdhsa_exception_fp_ieee_div_zero 0
		.amdhsa_exception_fp_ieee_overflow 0
		.amdhsa_exception_fp_ieee_underflow 0
		.amdhsa_exception_fp_ieee_inexact 0
		.amdhsa_exception_int_div_zero 0
	.end_amdhsa_kernel

amdhsa.kernels:
  - .agpr_count:     0
    .args:
      - .offset:         0
        .size:           192
        .value_kind:     by_value
      - .offset:         192
        .size:           4
        .value_kind:     hidden_block_count_x
      - .offset:         196
        .size:           4
        .value_kind:     hidden_block_count_y
      - .offset:         200
        .size:           4
        .value_kind:     hidden_block_count_z
      - .offset:         204
        .size:           2
        .value_kind:     hidden_group_size_x
      - .offset:         206
        .size:           2
        .value_kind:     hidden_group_size_y
      - .offset:         208
        .size:           2
        .value_kind:     hidden_group_size_z
      - .offset:         210
        .size:           2
        .value_kind:     hidden_remainder_x
      - .offset:         212
        .size:           2
        .value_kind:     hidden_remainder_y
      - .offset:         214
        .size:           2
        .value_kind:     hidden_remainder_z
      - .offset:         232
        .size:           8
        .value_kind:     hidden_global_offset_x
      - .offset:         240
        .size:           8
        .value_kind:     hidden_global_offset_y
      - .offset:         248
        .size:           8
        .value_kind:     hidden_global_offset_z
      - .offset:         256
        .size:           2
        .value_kind:     hidden_grid_dims
      - .offset:         280
        .size:           8
        .value_kind:     hidden_multigrid_sync_arg
      - .offset:         312
        .size:           4
        .value_kind:     hidden_dynamic_lds_size
    .group_segment_fixed_size: 0
    .kernarg_segment_align: 8
    .kernarg_segment_size: 448
    .language:       OpenCL C
    .language_version:
      - 2
      - 0
    .max_flat_workgroup_size: 512
    .name:           _Z4mega6Params
    .private_segment_fixed_size: 0
    .sgpr_count:     106
    .sgpr_spill_count: 107
    .symbol:         _Z4mega6Params.kd
    .uniform_work_group_size: 1
    .uses_dynamic_stack: false
    .vgpr_count:     256
    .vgpr_spill_count: 0
    .wavefront_size: 64
